# diff-attention tile loop keeps its four K/V stream pointers in registers (no per-tile 64-bit literal adds), on top of the previous stack
# speedup vs baseline: 1.0007x; 1.0007x over previous
; DI int tid() { int t; asm volatile("v_mov_b32 %0, %1" : "=v"(t) : "v"((int)threadIdx.x)); return t; }
; template <int DV, int MODE>
; DI void attn_item(const AttnArgs& a, char* smem) {
;     ...
;   const int t = tid(), lane = t & 63, w = __builtin_amdgcn_readfirstlane(t >> 6), r = lane & 31, h = lane >> 5;
;   constexpr int NDV = DV / 32;
;   constexpr int NVL = DV / 64;
;   const int nt = a.n0 + a.n1;
;   const int qrow = (MODE == 1) ? ((w & 3) * 32 + r) : (w * 32 + r);
;   const int qcoff = (MODE == 1) ? ((w >> 2) * 64) : 0;
;   u16* qp = a.qo + (size_t)qrow * 1024;
;   bf8 qf[4];
; #pragma unroll
;   for (int ks = 0; ks < 4; ++ks) qf[ks] = *(const bf8*)(qp + qcoff + ks * 16 + h * 8);
;   const u16* Ks = (MODE == 1 && (w >> 2)) ? Ks2 : Ks1;
;   int rq = 0, qc = 0, cs = 0, rsw = 0;
;   if (MODE == 2) {
;     __syncthreads();
;     for (int e = t; e < 15 * 32; e += NTHR) {
;       const int dr = e >> 5, dc = e & 31;
;       rpbS[e] = (dc < 31) ? a.rpb[dr * 31 + dc] * LOG2E : 0.f;
;     }
;     rq = a.rq0 + (w >> 1);
;     qc = (w & 1) * 32 + r;
;     cs = qc - 8; cs = cs < 0 ? 0 : (cs > 48 ? 48 : cs);
;     rsw = rq - 4; rsw = rsw < 0 ? 0 : (rsw > 24 ? 24 : rsw);
;   }
;   f32x16 O[NDV];
; #pragma unroll
;   for (int d = 0; d < NDV; ++d)
; #pragma unroll
;     for (int i = 0; i < 16; ++i) O[d][i] = 0.f;
;   float m = -1e30f, lsum = 0.f;
;   u32x4 rk1, rk2, rv[NVL];
;   const int srow = t >> 3, sch = t & 7;
;     ...
;   if (nt > 0) ATTN_FETCH(0)
; DI void phase_attn(const Params& p, int l, char* smem) {
;     ...
;       } else {
;         const int id2 = id - 2048 - 128;
;         const int qb = id2 & 1, g = id2 >> 1, b = g >> 2, j = g & 3;
;         a.qo = QO + (size_t)(NLAT + b * 256 + qb * 128) * 1024 + 512 + j * 128;
;         a.k1 = Kb + ((size_t)b * 16 + 8 + 2 * j) * T * 64;
;         a.k2 = Kb + ((size_t)b * 16 + 8 + 2 * j + 1) * T * 64;
;         a.vt = VT + ((size_t)b * 1024 + 512 + j * 128) * T;
;         a.s0 = 0; a.n0 = 0; a.n1 = 4;
;         attn_item<128, 1>(a, smem);
.LBB0_434:
	s_cmpk_gt_i32 s39, 0x3ff
	s_mov_b64 s[2:3], -1
	s_cbranch_scc0 .LBB0_551
	s_lshr_b32 s8, s39, 1
	s_cmpk_gt_u32 s39, 0x7ff
	s_cbranch_scc0 .LBB0_457
	s_cmpk_gt_u32 s39, 0x87f
	s_cbranch_scc0 .LBB0_448
	s_add_i32 s0, s39, 0xfffff780
	s_lshr_b32 s2, s0, 3
	s_lshl_b32 s3, s39, 7
	s_lshl_b32 s0, s2, 8
	s_and_b32 s3, s3, 0x80
	s_or_b32 s0, s0, s3
	s_add_i32 s0, s0, 0x8000
	s_lshr_b32 s9, s31, 3
	s_and_b32 s16, s8, 3
	s_bfe_u32 s14, s39, 0x20001
	s_lshl_b64 s[10:11], s[0:1], 11
	s_add_u32 s0, s20, s10
	s_addc_u32 s3, s21, s11
	s_lshl_b32 s15, s14, 7
	s_lshl_b32 s10, s14, 8
	s_add_u32 s10, s0, s10
	s_addc_u32 s11, s3, 0
	s_mov_b32 s3, s1
	s_lshl_b64 s[12:13], s[2:3], 4
	s_lshl_b32 s0, s14, 1
	s_or_b32 s0, s12, s0
	s_mul_i32 s12, s0, 0x48000
	s_mul_hi_u32 s0, s0, 0x48000
	s_mul_i32 s13, s13, 0x48000
	s_add_i32 s0, s0, s13
	v_readlane_b32 s18, v235, 50
	v_readlane_b32 s19, v235, 51
	s_add_u32 s12, s18, s12
	s_addc_u32 s13, s19, s0
	s_lshl_b64 s[2:3], s[2:3], 10
	s_or_b32 s0, s2, s15
	s_mul_i32 s2, s0, 0x1200
	s_mul_hi_u32 s0, s0, 0x1200
	s_mulk_i32 s3, 0x1200
	s_add_i32 s0, s0, s3
	v_readlane_b32 s14, v235, 48
	v_readlane_b32 s15, v235, 49
	s_add_u32 s2, s14, s2
	v_mov_b32 v10, v163
	s_addc_u32 s3, s15, s0
	v_readfirstlane_b32 s17, v10
	s_ashr_i32 s0, s17, 6
	s_lshl_b32 s14, s0, 5
	v_and_b32_e32 v137, 31, v10
	s_and_b32 s14, s14, 0x60
	v_or_b32_e32 v0, s14, v137
	s_ashr_i32 s14, s17, 2
	s_andn2_b32 s14, s14, 63
	v_lshlrev_b32_e32 v0, 11, v0
	v_bfe_u32 v143, v10, 5, 1
	v_lshl_add_u64 v[134:135], s[10:11], 0, v[0:1]
	s_ashr_i32 s15, s14, 31
	v_lshl_add_u64 v[2:3], s[14:15], 1, v[134:135]
	v_lshlrev_b32_e32 v132, 4, v143
	v_mov_b32_e32 v133, v1
	v_lshl_add_u64 v[2:3], v[2:3], 0, v[132:133]
	global_load_dwordx4 v[98:101], v[2:3], off offset:1024
	global_load_dwordx4 v[102:105], v[2:3], off offset:1056
	global_load_dwordx4 v[106:109], v[2:3], off offset:1088
	global_load_dwordx4 v[110:113], v[2:3], off offset:1120
	v_ashrrev_i32_e32 v2, 3, v10
	v_ashrrev_i32_e32 v3, 31, v2
	v_lshlrev_b32_e32 v0, 4, v10
	v_lshlrev_b64 v[4:5], 7, v[2:3]
	v_and_b32_e32 v0, 0x70, v0
	v_lshl_add_u64 v[6:7], s[12:13], 0, v[4:5]
	v_lshl_add_u64 v[6:7], v[6:7], 0, v[0:1]
	s_mov_b32 s10, 0x280000
	v_add_co_u32_e32 v8, vcc, s10, v6
	s_mov_b32 s10, 0x2c8000
	s_nop 0
	v_addc_co_u32_e32 v9, vcc, 0, v7, vcc
	v_add_co_u32_e32 v6, vcc, s10, v6
	v_add_u32_e32 v3, 64, v2
	s_nop 0
	v_addc_co_u32_e32 v7, vcc, 0, v7, vcc
	global_load_dwordx4 v[114:117], v[8:9], off
	global_load_dwordx4 v[118:121], v[6:7], off
	v_lshl_add_u64 v[6:7], s[2:3], 0, v[0:1]
	s_mov_b64 s[2:3], 0x241000
	v_lshl_add_u64 v[6:7], v[6:7], 0, s[2:3]
	v_mad_i64_i32 v[8:9], s[2:3], v2, s77, v[6:7]
	v_mad_i64_i32 v[6:7], s[2:3], v3, s77, v[6:7]
	global_load_dwordx4 v[122:125], v[8:9], off
	global_load_dwordx4 v[126:129], v[6:7], off
	s_mul_hi_u32 s3, s9, 0x480000
	s_mul_i32 s9, s9, 0x480000
	s_mul_i32 s16, s16, 0x90000
	s_cmpk_lt_u32 s17, 0x100
	s_cselect_b32 s10, 0, 0x2400
	s_add_u32 s9, s9, s16
	s_addc_u32 s3, s3, 0
	v_or_b32_e32 v18, s10, v132
	s_add_u32 s10, s58, s9
	v_and_b32_e32 v3, 63, v10
	v_mul_lo_u32 v6, v2, s78
	s_addc_u32 s11, s59, s3
	v_lshlrev_b32_e32 v136, 3, v143
	v_add_u32_e32 v144, v0, v6
	v_lshlrev_b32_e32 v0, 2, v3
	v_mul_u32_u24_e32 v19, 0x90, v137
	v_mov_b64_e32 v[6:7], s[10:11]
	v_mov_b32_e32 v16, v1
	v_mov_b32_e32 v17, v1
	v_xor_b32_e32 v133, 0x80, v0
	v_and_b32_e32 v0, 7, v10
	v_mad_i64_i32 v[138:139], s[12:13], v2, s77, v[6:7]
	v_lshl_add_u64 v[140:141], s[10:11], 0, v[4:5]
	v_mov_b32_e32 v2, v1
	v_mov_b32_e32 v3, v1
	v_mov_b32_e32 v4, v1
	v_mov_b32_e32 v5, v1
	v_mov_b32_e32 v6, v1
	v_mov_b32_e32 v7, v1
	v_mov_b32_e32 v8, v1
	v_mov_b32_e32 v9, v1
	v_mov_b32_e32 v10, v1
	v_mov_b32_e32 v11, v1
	v_mov_b32_e32 v12, v1
	v_mov_b32_e32 v13, v1
	v_mov_b32_e32 v14, v1
	v_mov_b32_e32 v15, v1
	v_add_u32_e32 v146, v18, v19
	v_add_u32_e32 v147, v136, v19
	v_mov_b64_e32 v[32:33], v[16:17]
	v_mov_b64_e32 v[48:49], v[16:17]
	v_mov_b64_e32 v[64:65], v[16:17]
	s_mov_b32 s2, 0
	v_lshlrev_b32_e32 v0, 4, v0
	v_mov_b32_e32 v145, 0
	v_mov_b32_e32 v148, 0xf149f2ca
	v_mov_b64_e32 v[30:31], v[14:15]
	v_mov_b64_e32 v[28:29], v[12:13]
	v_mov_b64_e32 v[26:27], v[10:11]
	v_mov_b64_e32 v[24:25], v[8:9]
	v_mov_b64_e32 v[22:23], v[6:7]
	v_mov_b64_e32 v[20:21], v[4:5]
	v_mov_b64_e32 v[18:19], v[2:3]
	v_mov_b64_e32 v[46:47], v[14:15]
	v_mov_b64_e32 v[44:45], v[12:13]
	v_mov_b64_e32 v[42:43], v[10:11]
	v_mov_b64_e32 v[40:41], v[8:9]
	v_mov_b64_e32 v[38:39], v[6:7]
	v_mov_b64_e32 v[36:37], v[4:5]
	v_mov_b64_e32 v[34:35], v[2:3]
	v_mov_b64_e32 v[62:63], v[14:15]
	v_mov_b64_e32 v[60:61], v[12:13]
	v_mov_b64_e32 v[58:59], v[10:11]
	v_mov_b64_e32 v[56:57], v[8:9]
	v_mov_b64_e32 v[54:55], v[6:7]
	v_mov_b64_e32 v[52:53], v[4:5]
	v_mov_b64_e32 v[50:51], v[2:3]
	v_lshl_add_u64 v[238:239], v[140:141], 0, v[0:1]
	v_lshl_add_u64 v[242:243], v[138:139], 0, v[0:1]
	s_mov_b32 s101, 0
	s_mov_b32 s100, 0x13864100
	v_lshl_add_u64 v[240:241], v[238:239], 0, s[100:101]
	s_mov_b32 s100, 0x1381c100
	v_lshl_add_u64 v[238:239], v[238:239], 0, s[100:101]
	s_mov_b32 s100, 0x18023180
	v_lshl_add_u64 v[244:245], v[242:243], 0, s[100:101]
	s_mov_b32 s100, 0x17fdb180
	v_lshl_add_u64 v[242:243], v[242:243], 0, s[100:101]
	s_branch .LBB0_439
; DI unsigned pack2(float a, float b) { f2 v = {a, b}; bf2 r = __builtin_convertvector(v, bf2); return __builtin_bit_cast(unsigned, r); }
; DI f32x16 mfma32(bf8 a, bf8 b, f32x16 c) { return __builtin_amdgcn_mfma_f32_32x32x16_bf16(a, b, c, 0, 0, 0); }
; DI float ex2(float x) { return __builtin_amdgcn_exp2f(x); }
; DI float shx(float v, int lane, int mask) { return __int_as_float(__builtin_amdgcn_ds_bpermute((lane ^ mask) << 2, __float_as_int(v))); }
; template <int DV, int MODE>
; DI void attn_item(const AttnArgs& a, char* smem) {
;     ...
;       mx = fmaxf(mx, shx(mx, lane, 32)) * SC;
;       const float mn = fmaxf(m, mx);
;       const bool resc = __builtin_amdgcn_ballot_w64(mn != m) != 0ull;
;       float ps0 = 0.f, ps1 = 0.f;
; #pragma unroll
;       for (int kb = 0; kb < 2; ++kb)
; #pragma unroll
;         for (int i = 0; i < 16; i += 2) {
;           f32x2n v = {s[kb][i], s[kb][i + 1]};
;           v = v * f32x2n{SC, SC} - f32x2n{mn, mn};
;           const float p0 = ex2(v.x), p1 = ex2(v.y);
;           s[kb][i] = p0; s[kb][i + 1] = p1;
;           ps0 += p0; ps1 += p1;
;         }
;       if (resc) {
;         const float alpha = ex2(m - mn);
;         m = mn;
;         lsum *= alpha;
; #pragma unroll
;         for (int d = 0; d < NDV; ++d)
; #pragma unroll
;           for (int i = 0; i < 16; ++i) O[d][i] *= alpha;
;       }
;       lsum += ps0 + ps1;
; #pragma unroll
;       for (int kb = 0; kb < 2; ++kb)
; #pragma unroll
;         for (int s2 = 0; s2 < 2; ++s2) {
;           u32x4 pk;
;           pk.x = pack2(s[kb][s2 * 8 + 0], s[kb][s2 * 8 + 1]);
;           pk.y = pack2(s[kb][s2 * 8 + 2], s[kb][s2 * 8 + 3]);
;           pk.z = pack2(s[kb][s2 * 8 + 4], s[kb][s2 * 8 + 5]);
;           pk.w = pack2(s[kb][s2 * 8 + 6], s[kb][s2 * 8 + 7]);
;           const bf8 pf = __builtin_bit_cast(bf8, pk);
; #pragma unroll
;           for (int d = 0; d < NDV; ++d) {
;             const u16* vp = Vs + (d * 32 + r) * 72 + kb * 32 + s2 * 16 + 4 * h;
;             u32x4 vv;
;             const u32x2 lo = *(const u32x2*)(vp);
;             const u32x2 hi = *(const u32x2*)(vp + 8);
;             vv.x = lo.x; vv.y = lo.y; vv.z = hi.x; vv.w = hi.y;
;             O[d] = mfma32(__builtin_bit_cast(bf8, vv), pf, O[d]);
;           }
;         }
.LBB0_438:
	v_pk_fma_f32 v[82:83], v[82:83], s[24:25], v[142:143] op_sel_hi:[1,0,0] neg_lo:[0,0,1] neg_hi:[0,0,1]
	v_pk_fma_f32 v[66:67], v[66:67], s[24:25], v[142:143] op_sel_hi:[1,0,0] neg_lo:[0,0,1] neg_hi:[0,0,1]
	v_exp_f32_e32 v150, v82
	v_exp_f32_e32 v151, v83
	v_pk_fma_f32 v[82:83], v[84:85], s[24:25], v[142:143] op_sel_hi:[1,0,0] neg_lo:[0,0,1] neg_hi:[0,0,1]
	s_mov_b64 s[10:11], 0x80
	v_exp_f32_e32 v84, v82
	v_exp_f32_e32 v85, v83
	v_pk_fma_f32 v[82:83], v[86:87], s[24:25], v[142:143] op_sel_hi:[1,0,0] neg_lo:[0,0,1] neg_hi:[0,0,1]
	v_add_f32_e32 v152, 0, v150
	v_exp_f32_e32 v86, v82
	v_exp_f32_e32 v87, v83
	v_pk_fma_f32 v[82:83], v[88:89], s[24:25], v[142:143] op_sel_hi:[1,0,0] neg_lo:[0,0,1] neg_hi:[0,0,1]
	v_add_f32_e32 v153, 0, v151
	v_exp_f32_e32 v88, v82
	v_exp_f32_e32 v89, v83
	v_pk_fma_f32 v[82:83], v[90:91], s[24:25], v[142:143] op_sel_hi:[1,0,0] neg_lo:[0,0,1] neg_hi:[0,0,1]
	v_add_f32_e32 v152, v84, v152
	v_exp_f32_e32 v90, v82
	v_exp_f32_e32 v91, v83
	v_pk_fma_f32 v[82:83], v[92:93], s[24:25], v[142:143] op_sel_hi:[1,0,0] neg_lo:[0,0,1] neg_hi:[0,0,1]
	v_add_f32_e32 v153, v85, v153
	v_exp_f32_e32 v92, v82
	v_exp_f32_e32 v93, v83
	v_pk_fma_f32 v[82:83], v[94:95], s[24:25], v[142:143] op_sel_hi:[1,0,0] neg_lo:[0,0,1] neg_hi:[0,0,1]
	v_add_f32_e32 v152, v86, v152
	v_add_f32_e32 v153, v87, v153
	v_exp_f32_e32 v94, v82
	v_exp_f32_e32 v95, v83
	v_pk_fma_f32 v[82:83], v[96:97], s[24:25], v[142:143] op_sel_hi:[1,0,0] neg_lo:[0,0,1] neg_hi:[0,0,1]
	v_add_f32_e32 v152, v88, v152
	v_add_f32_e32 v153, v89, v153
	v_exp_f32_e32 v96, v82
	v_exp_f32_e32 v97, v83
	v_add_f32_e32 v152, v90, v152
	v_add_f32_e32 v153, v91, v153
	v_add_f32_e32 v152, v92, v152
	v_add_f32_e32 v153, v93, v153
	v_add_f32_e32 v152, v94, v152
	v_add_f32_e32 v153, v95, v153
	v_add_f32_e32 v82, v96, v152
	v_add_f32_e32 v83, v97, v153
	v_exp_f32_e32 v152, v66
	v_exp_f32_e32 v153, v67
	v_pk_fma_f32 v[66:67], v[68:69], s[24:25], v[142:143] op_sel_hi:[1,0,0] neg_lo:[0,0,1] neg_hi:[0,0,1]
	s_add_i32 s2, s2, 1
	v_exp_f32_e32 v154, v66
	v_exp_f32_e32 v155, v67
	v_pk_fma_f32 v[66:67], v[70:71], s[24:25], v[142:143] op_sel_hi:[1,0,0] neg_lo:[0,0,1] neg_hi:[0,0,1]
	v_add_f32_e32 v82, v152, v82
	v_exp_f32_e32 v156, v66
	v_exp_f32_e32 v157, v67
	v_pk_fma_f32 v[66:67], v[72:73], s[24:25], v[142:143] op_sel_hi:[1,0,0] neg_lo:[0,0,1] neg_hi:[0,0,1]
	v_add_f32_e32 v83, v153, v83
	v_exp_f32_e32 v158, v66
	v_exp_f32_e32 v159, v67
	v_pk_fma_f32 v[66:67], v[74:75], s[24:25], v[142:143] op_sel_hi:[1,0,0] neg_lo:[0,0,1] neg_hi:[0,0,1]
	v_add_f32_e32 v68, v154, v82
	v_exp_f32_e32 v71, v66
	v_exp_f32_e32 v72, v67
	v_pk_fma_f32 v[66:67], v[76:77], s[24:25], v[142:143] op_sel_hi:[1,0,0] neg_lo:[0,0,1] neg_hi:[0,0,1]
	v_add_f32_e32 v69, v155, v83
	v_exp_f32_e32 v73, v66
	v_exp_f32_e32 v74, v67
	v_pk_fma_f32 v[66:67], v[78:79], s[24:25], v[142:143] op_sel_hi:[1,0,0] neg_lo:[0,0,1] neg_hi:[0,0,1]
	v_add_f32_e32 v68, v156, v68
	v_add_f32_e32 v69, v157, v69
	v_exp_f32_e32 v75, v66
	v_exp_f32_e32 v76, v67
	v_pk_fma_f32 v[66:67], v[80:81], s[24:25], v[142:143] op_sel_hi:[1,0,0] neg_lo:[0,0,1] neg_hi:[0,0,1]
	v_add_f32_e32 v68, v158, v68
	v_add_f32_e32 v69, v159, v69
	v_exp_f32_e32 v77, v66
	v_exp_f32_e32 v78, v67
	v_add_f32_e32 v68, v71, v68
	v_add_f32_e32 v69, v72, v69
	v_add_f32_e32 v68, v73, v68
	v_add_f32_e32 v69, v74, v69
	v_add_f32_e32 v68, v75, v68
	v_add_f32_e32 v69, v76, v69
	v_add_f32_e32 v66, v77, v68
	v_add_f32_e32 v67, v78, v69
	v_add_u32_e32 v79, 0x4800, v147
	v_add_f32_e32 v70, v66, v67
	v_cvt_pk_bf16_f32 v67, v84, v85
	v_cvt_pk_bf16_f32 v68, v86, v87
	ds_read2_b64 v[80:83], v79 offset1:2
	ds_read2_b64 v[84:87], v79 offset0:4 offset1:6
	v_cvt_pk_bf16_f32 v66, v150, v151
	v_cvt_pk_bf16_f32 v69, v88, v89
	v_add_u32_e32 v88, 0x5800, v147
	v_add_u32_e32 v89, 0x6800, v147
	s_waitcnt lgkmcnt(1)
	v_mfma_f32_32x32x16_bf16 v[50:65], v[80:83], v[66:69], v[50:65]
	ds_read2_b64 v[80:83], v88 offset0:64 offset1:66
	v_add_u32_e32 v142, 0x7800, v147
	s_mov_b64 s[10:11], 0x2000
	v_add_f32_e32 v145, v70, v145
	s_cmp_eq_u32 s2, 4
	s_waitcnt lgkmcnt(0)
	v_mfma_f32_32x32x16_bf16 v[34:49], v[80:83], v[66:69], v[34:49]
	ds_read2_b64 v[80:83], v89 offset0:128 offset1:130
	s_waitcnt lgkmcnt(0)
	v_mfma_f32_32x32x16_bf16 v[18:33], v[80:83], v[66:69], v[18:33]
	ds_read2_b64 v[80:83], v142 offset0:192 offset1:194
	s_waitcnt lgkmcnt(0)
	v_mfma_f32_32x32x16_bf16 v[2:17], v[80:83], v[66:69], v[2:17]
	ds_read2_b64 v[80:83], v88 offset0:68 offset1:70
	v_cvt_pk_bf16_f32 v66, v90, v91
	v_cvt_pk_bf16_f32 v67, v92, v93
	v_cvt_pk_bf16_f32 v68, v94, v95
	v_cvt_pk_bf16_f32 v69, v96, v97
	s_waitcnt lgkmcnt(0)
	s_nop 0
	v_mfma_f32_32x32x16_bf16 v[34:49], v[80:83], v[66:69], v[34:49]
	ds_read2_b64 v[80:83], v89 offset0:132 offset1:134
	s_waitcnt lgkmcnt(0)
	v_mfma_f32_32x32x16_bf16 v[18:33], v[80:83], v[66:69], v[18:33]
	ds_read2_b64 v[80:83], v142 offset0:196 offset1:198
	s_waitcnt lgkmcnt(0)
	v_mfma_f32_32x32x16_bf16 v[2:17], v[80:83], v[66:69], v[2:17]
	ds_read2_b64 v[80:83], v79 offset0:8 offset1:10
	v_mfma_f32_32x32x16_bf16 v[50:65], v[84:87], v[66:69], v[50:65]
	v_cvt_pk_bf16_f32 v66, v152, v153
	v_cvt_pk_bf16_f32 v67, v154, v155
	v_cvt_pk_bf16_f32 v68, v156, v157
	v_cvt_pk_bf16_f32 v69, v158, v159
	s_waitcnt lgkmcnt(0)
	s_nop 0
	v_mfma_f32_32x32x16_bf16 v[50:65], v[80:83], v[66:69], v[50:65]
	ds_read2_b64 v[80:83], v88 offset0:72 offset1:74
	s_waitcnt lgkmcnt(0)
	v_mfma_f32_32x32x16_bf16 v[34:49], v[80:83], v[66:69], v[34:49]
	ds_read2_b64 v[80:83], v89 offset0:136 offset1:138
	s_waitcnt lgkmcnt(0)
	v_mfma_f32_32x32x16_bf16 v[18:33], v[80:83], v[66:69], v[18:33]
	ds_read2_b64 v[80:83], v142 offset0:200 offset1:202
	s_waitcnt lgkmcnt(0)
	v_mfma_f32_32x32x16_bf16 v[2:17], v[80:83], v[66:69], v[2:17]
	v_cvt_pk_bf16_f32 v66, v71, v72
	v_cvt_pk_bf16_f32 v67, v73, v74
	v_cvt_pk_bf16_f32 v68, v75, v76
	ds_read2_b64 v[72:75], v79 offset0:12 offset1:14
	v_cvt_pk_bf16_f32 v69, v77, v78
	s_waitcnt lgkmcnt(0)
	s_nop 0
	v_mfma_f32_32x32x16_bf16 v[50:65], v[72:75], v[66:69], v[50:65]
	ds_read2_b64 v[72:75], v88 offset0:76 offset1:78
	s_waitcnt lgkmcnt(0)
	v_mfma_f32_32x32x16_bf16 v[34:49], v[72:75], v[66:69], v[34:49]
	ds_read2_b64 v[72:75], v89 offset0:140 offset1:142
	s_waitcnt lgkmcnt(0)
	v_mfma_f32_32x32x16_bf16 v[18:33], v[72:75], v[66:69], v[18:33]
	ds_read2_b64 v[72:75], v142 offset0:204 offset1:206
	s_waitcnt lgkmcnt(0)
	v_mfma_f32_32x32x16_bf16 v[2:17], v[72:75], v[66:69], v[2:17]
	s_cbranch_scc1 .LBB0_443
; template <int DV, int MODE>
; DI void attn_item(const AttnArgs& a, char* smem) {
;     ...
;   if (nt > 0) ATTN_FETCH(0)
;   for (int tt = 0; tt < nt; ++tt) {
;     __syncthreads();
;     *(u32x4*)(Ks1 + srow * 72 + sch * 8) = rk1;
;     if (MODE == 1) *(u32x4*)(Ks2 + srow * 72 + sch * 8) = rk2;
; #pragma unroll
;     for (int j = 0; j < NVL; ++j) *(u32x4*)(Vs + (srow + 64 * j) * 72 + sch * 8) = rv[j];
;     __syncthreads();
;     if (tt + 1 < nt) ATTN_FETCH(tt + 1)
.LBB0_439:
	s_cmp_gt_u32 s2, 2
	s_barrier
	s_waitcnt vmcnt(3)
	ds_write_b128 v144, v[114:117]
	s_waitcnt vmcnt(2)
	ds_write_b128 v144, v[118:121] offset:9216
	s_waitcnt vmcnt(1)
	ds_write_b128 v144, v[122:125] offset:18432
	s_waitcnt vmcnt(0)
	ds_write_b128 v144, v[126:129] offset:27648
	s_waitcnt lgkmcnt(0)
	s_barrier
	s_cbranch_scc1 .LBB0_441
	global_load_dwordx4 v[114:117], v[238:239], off
	global_load_dwordx4 v[118:121], v[240:241], off
	global_load_dwordx4 v[122:125], v[242:243], off
	global_load_dwordx4 v[126:129], v[244:245], off
	s_mov_b64 s[100:101], 0x2000
	v_lshl_add_u64 v[238:239], v[238:239], 0, s[100:101]
	v_lshl_add_u64 v[240:241], v[240:241], 0, s[100:101]
	s_mov_b64 s[100:101], 0x80
	v_lshl_add_u64 v[242:243], v[242:243], 0, s[100:101]
	v_lshl_add_u64 v[244:245], v[244:245], 0, s[100:101]
